# attention hot QK block: second accumulator shift-init moved behind the first MFMA (shorter VALU-only head)
# speedup vs baseline: 1.0148x; 1.0058x over previous
.LBB0_883:
	s_andn2_b64 vcc, exec, s[28:29]
	s_cbranch_vccnz .LBB0_885
	v_mad_u32_u24 v203, v203, s82, v201
	ds_read_b128 v[204:207], v203
	ds_read_b128 v[208:211], v203 offset:32
	s_nop 5
	v_xor_b32_e32 v80, 0x80000000, v199
	v_mov_b32_e32 v81, v80
	v_mov_b32_e32 v82, v80
	v_mov_b32_e32 v83, v80
	v_mov_b32_e32 v84, v80
	v_mov_b32_e32 v85, v80
	v_mov_b32_e32 v86, v80
	v_mov_b32_e32 v87, v80
	v_mov_b32_e32 v88, v80
	v_mov_b32_e32 v89, v80
	v_mov_b32_e32 v90, v80
	v_mov_b32_e32 v91, v80
	v_mov_b32_e32 v92, v80
	v_mov_b32_e32 v93, v80
	v_mov_b32_e32 v94, v80
	v_mov_b32_e32 v95, v80
	s_waitcnt lgkmcnt(0)
	v_mfma_f32_32x32x16_bf16 v[80:95], v[204:207], v[96:99], v[80:95]
	v_xor_b32_e32 v64, 0x80000000, v200
	v_mov_b32_e32 v65, v64
	v_mov_b32_e32 v66, v64
	v_mov_b32_e32 v67, v64
	v_mov_b32_e32 v68, v64
	v_mov_b32_e32 v69, v64
	v_mov_b32_e32 v70, v64
	v_mov_b32_e32 v71, v64
	v_mov_b32_e32 v72, v64
	v_mov_b32_e32 v73, v64
	v_mov_b32_e32 v74, v64
	v_mov_b32_e32 v75, v64
	v_mov_b32_e32 v76, v64
	v_mov_b32_e32 v77, v64
	v_mov_b32_e32 v78, v64
	v_mov_b32_e32 v79, v64
	v_mfma_f32_32x32x16_bf16 v[64:79], v[204:207], v[136:139], v[64:79]
	v_mfma_f32_32x32x16_bf16 v[80:95], v[208:211], v[100:103], v[80:95]
	v_mfma_f32_32x32x16_bf16 v[64:79], v[208:211], v[120:123], v[64:79]
	ds_read_b128 v[204:207], v203 offset:64
	ds_read_b128 v[208:211], v203 offset:96
	s_waitcnt lgkmcnt(0)
	v_mfma_f32_32x32x16_bf16 v[80:95], v[204:207], v[104:107], v[80:95]
	v_mfma_f32_32x32x16_bf16 v[64:79], v[204:207], v[124:127], v[64:79]
	v_mfma_f32_32x32x16_bf16 v[80:95], v[208:211], v[108:111], v[80:95]
	v_mfma_f32_32x32x16_bf16 v[64:79], v[208:211], v[128:131], v[64:79]
	ds_read_b128 v[204:207], v203 offset:128
	ds_read_b128 v[208:211], v203 offset:160
	s_waitcnt lgkmcnt(0)
	v_mfma_f32_32x32x16_bf16 v[80:95], v[204:207], v[112:115], v[80:95]
	v_mfma_f32_32x32x16_bf16 v[64:79], v[204:207], v[132:135], v[64:79]
	v_mfma_f32_32x32x16_bf16 v[80:95], v[208:211], v[116:119], v[80:95]
	v_mfma_f32_32x32x16_bf16 v[64:79], v[208:211], v[140:143], v[64:79]
	s_branch .LBB0_885

.LBB0_2117:
	s_andn2_b64 vcc, exec, s[34:35]
	s_cbranch_vccnz .LBB0_2119
	v_mad_u32_u24 v203, v203, s81, v201
	ds_read_b128 v[204:207], v203
	ds_read_b128 v[208:211], v203 offset:32
	s_nop 5
	v_xor_b32_e32 v80, 0x80000000, v199
	v_mov_b32_e32 v81, v80
	v_mov_b32_e32 v82, v80
	v_mov_b32_e32 v83, v80
	v_mov_b32_e32 v84, v80
	v_mov_b32_e32 v85, v80
	v_mov_b32_e32 v86, v80
	v_mov_b32_e32 v87, v80
	v_mov_b32_e32 v88, v80
	v_mov_b32_e32 v89, v80
	v_mov_b32_e32 v90, v80
	v_mov_b32_e32 v91, v80
	v_mov_b32_e32 v92, v80
	v_mov_b32_e32 v93, v80
	v_mov_b32_e32 v94, v80
	v_mov_b32_e32 v95, v80
	s_waitcnt lgkmcnt(0)
	v_mfma_f32_32x32x16_bf16 v[80:95], v[204:207], v[96:99], v[80:95]
	v_xor_b32_e32 v64, 0x80000000, v200
	v_mov_b32_e32 v65, v64
	v_mov_b32_e32 v66, v64
	v_mov_b32_e32 v67, v64
	v_mov_b32_e32 v68, v64
	v_mov_b32_e32 v69, v64
	v_mov_b32_e32 v70, v64
	v_mov_b32_e32 v71, v64
	v_mov_b32_e32 v72, v64
	v_mov_b32_e32 v73, v64
	v_mov_b32_e32 v74, v64
	v_mov_b32_e32 v75, v64
	v_mov_b32_e32 v76, v64
	v_mov_b32_e32 v77, v64
	v_mov_b32_e32 v78, v64
	v_mov_b32_e32 v79, v64
	v_mfma_f32_32x32x16_bf16 v[64:79], v[204:207], v[136:139], v[64:79]
	v_mfma_f32_32x32x16_bf16 v[80:95], v[208:211], v[100:103], v[80:95]
	v_mfma_f32_32x32x16_bf16 v[64:79], v[208:211], v[120:123], v[64:79]
	ds_read_b128 v[204:207], v203 offset:64
	ds_read_b128 v[208:211], v203 offset:96
	s_waitcnt lgkmcnt(0)
	v_mfma_f32_32x32x16_bf16 v[80:95], v[204:207], v[104:107], v[80:95]
	v_mfma_f32_32x32x16_bf16 v[64:79], v[204:207], v[124:127], v[64:79]
	v_mfma_f32_32x32x16_bf16 v[80:95], v[208:211], v[108:111], v[80:95]
	v_mfma_f32_32x32x16_bf16 v[64:79], v[208:211], v[128:131], v[64:79]
	ds_read_b128 v[204:207], v203 offset:128
	ds_read_b128 v[208:211], v203 offset:160
	s_waitcnt lgkmcnt(0)
	v_mfma_f32_32x32x16_bf16 v[80:95], v[204:207], v[112:115], v[80:95]
	v_mfma_f32_32x32x16_bf16 v[64:79], v[204:207], v[132:135], v[64:79]
	v_mfma_f32_32x32x16_bf16 v[80:95], v[208:211], v[116:119], v[80:95]
	v_mfma_f32_32x32x16_bf16 v[64:79], v[208:211], v[140:143], v[64:79]
	s_branch .LBB0_2119
